# dn_prep solve: x-init 32 divergent serialized LDS reads replaced by batched ds_reads + wave-uniform scalar branch (bit-identical)
# speedup vs baseline: 1.0139x; 1.0139x over previous
; DI void dn_prep_item(const Params& p, int l, int item, int next_item, u32x4 (&pre)[12], unsigned char* lds, int tid) {
;     ...
;         if (wv < 5) {
;             const int half = (wv >= 2) ? 1 : 0, c = (wv < 2) ? tid : ((wv < 4) ? tid - 128 : (lane & 31)), r0 = 32 * half;
;             const float* Lb = Ls + r0 * 64 + r0;
;             float x[32];
;             if (wv < 4) {
; #pragma unroll
;                 for (int i = 0; i < 32; ++i) x[i] = (c < 64) ? BETAs[r0 + i] * Vs[(r0 + i) * 65 + c] : BETAs[r0 + i] * Ks[(r0 + i) * 65 + c - 64] * EGs[r0 + i];
;             } else {
; #pragma unroll
;                 for (int i = 0; i < 32; ++i) x[i] = Ls[(32 + i) * 64 + c];
;             }
.LBB0_363:
	s_or_saveexec_b64 s[8:9], s[8:9]
	v_mov_b64_e32 v[0:1], s[10:11]
	v_mov_b64_e32 v[58:59], s[6:7]
	s_xor_b64 exec, exec, s[8:9]
	s_cbranch_execz .LBB0_503
	v_add_u32_e32 v0, 0xffffff80, v54
	v_and_b32_e32 v31, 31, v54
	v_cmp_eq_u32_e64 s[6:7], 4, v60
	v_cmp_ne_u32_e32 vcc, 4, v60
	s_nop 0
	v_cndmask_b32_e64 v0, v0, v31, s[6:7]
	v_cmp_gt_i32_e64 s[6:7], 2, v60
	s_nop 1
	v_cndmask_b32_e64 v32, v0, v54, s[6:7]
	v_cmp_lt_i32_e64 s[6:7], 1, v60
	s_nop 1
	v_cndmask_b32_e64 v33, 0, 32, s[6:7]
	v_lshlrev_b32_e32 v0, 8, v33
	v_lshlrev_b32_e32 v1, 2, v33
	v_add3_u32 v35, v168, v0, v1
	s_and_saveexec_b64 s[6:7], vcc
	s_xor_b64 s[10:11], exec, s[6:7]
	s_cbranch_execz .LBB0_494
	s_movk_i32 s5, 0x41
	v_cmp_lt_i32_e64 s[12:13], 63, v32
	v_mad_u32_u24 v244, v33, s5, v32
	v_lshl_add_u32 v245, v33, 2, v69
	v_lshl_add_u32 v246, v33, 2, v70
	v_mov_b32_e32 v247, 0x8200
	v_mov_b32_e32 v248, 0x4000
	v_lshl_add_u32 v244, v244, 2, v168
	v_cndmask_b32_e64 v247, v247, v248, s[12:13]
	v_add_u32_e32 v244, v244, v247
	ds_read_b128 v[212:215], v245
	ds_read_b128 v[216:219], v245 offset:16
	ds_read_b128 v[220:223], v245 offset:32
	ds_read_b128 v[224:227], v245 offset:48
	ds_read_b128 v[228:231], v245 offset:64
	ds_read_b128 v[232:235], v245 offset:80
	ds_read_b128 v[236:239], v245 offset:96
	ds_read_b128 v[240:243], v245 offset:112
	ds_read_b32 v0, v244
	ds_read_b32 v1, v244 offset:260
	ds_read_b32 v2, v244 offset:520
	ds_read_b32 v3, v244 offset:780
	ds_read_b32 v4, v244 offset:1040
	ds_read_b32 v5, v244 offset:1300
	ds_read_b32 v6, v244 offset:1560
	ds_read_b32 v7, v244 offset:1820
	ds_read_b32 v8, v244 offset:2080
	ds_read_b32 v9, v244 offset:2340
	ds_read_b32 v10, v244 offset:2600
	ds_read_b32 v11, v244 offset:2860
	ds_read_b32 v12, v244 offset:3120
	ds_read_b32 v13, v244 offset:3380
	ds_read_b32 v14, v244 offset:3640
	ds_read_b32 v15, v244 offset:3900
	ds_read_b32 v16, v244 offset:4160
	ds_read_b32 v17, v244 offset:4420
	ds_read_b32 v18, v244 offset:4680
	ds_read_b32 v19, v244 offset:4940
	ds_read_b32 v20, v244 offset:5200
	ds_read_b32 v21, v244 offset:5460
	ds_read_b32 v22, v244 offset:5720
	ds_read_b32 v23, v244 offset:5980
	ds_read_b32 v24, v244 offset:6240
	ds_read_b32 v25, v244 offset:6500
	ds_read_b32 v26, v244 offset:6760
	ds_read_b32 v27, v244 offset:7020
	ds_read_b32 v36, v244 offset:7280
	ds_read_b32 v28, v244 offset:7540
	ds_read_b32 v29, v244 offset:7800
	ds_read_b32 v37, v244 offset:8060
	s_waitcnt lgkmcnt(0)
	v_mul_f32_e32 v0, v212, v0
	v_mul_f32_e32 v1, v213, v1
	v_mul_f32_e32 v2, v214, v2
	v_mul_f32_e32 v3, v215, v3
	v_mul_f32_e32 v4, v216, v4
	v_mul_f32_e32 v5, v217, v5
	v_mul_f32_e32 v6, v218, v6
	v_mul_f32_e32 v7, v219, v7
	v_mul_f32_e32 v8, v220, v8
	v_mul_f32_e32 v9, v221, v9
	v_mul_f32_e32 v10, v222, v10
	v_mul_f32_e32 v11, v223, v11
	v_mul_f32_e32 v12, v224, v12
	v_mul_f32_e32 v13, v225, v13
	v_mul_f32_e32 v14, v226, v14
	v_mul_f32_e32 v15, v227, v15
	v_mul_f32_e32 v16, v228, v16
	v_mul_f32_e32 v17, v229, v17
	v_mul_f32_e32 v18, v230, v18
	v_mul_f32_e32 v19, v231, v19
	v_mul_f32_e32 v20, v232, v20
	v_mul_f32_e32 v21, v233, v21
	v_mul_f32_e32 v22, v234, v22
	v_mul_f32_e32 v23, v235, v23
	v_mul_f32_e32 v24, v236, v24
	v_mul_f32_e32 v25, v237, v25
	v_mul_f32_e32 v26, v238, v26
	v_mul_f32_e32 v27, v239, v27
	v_mul_f32_e32 v36, v240, v36
	v_mul_f32_e32 v28, v241, v28
	v_mul_f32_e32 v29, v242, v29
	v_mul_f32_e32 v37, v243, v37
	s_cmp_eq_u64 s[12:13], 0
	s_cbranch_scc1 .Lxinit_done
	ds_read_b128 v[212:215], v246
	ds_read_b128 v[216:219], v246 offset:16
	ds_read_b128 v[220:223], v246 offset:32
	ds_read_b128 v[224:227], v246 offset:48
	ds_read_b128 v[228:231], v246 offset:64
	ds_read_b128 v[232:235], v246 offset:80
	ds_read_b128 v[236:239], v246 offset:96
	ds_read_b128 v[240:243], v246 offset:112
	s_waitcnt lgkmcnt(0)
	v_mul_f32_e32 v0, v0, v212
	v_mul_f32_e32 v1, v1, v213
	v_mul_f32_e32 v2, v2, v214
	v_mul_f32_e32 v3, v3, v215
	v_mul_f32_e32 v4, v4, v216
	v_mul_f32_e32 v5, v5, v217
	v_mul_f32_e32 v6, v6, v218
	v_mul_f32_e32 v7, v7, v219
	v_mul_f32_e32 v8, v8, v220
	v_mul_f32_e32 v9, v9, v221
	v_mul_f32_e32 v10, v10, v222
	v_mul_f32_e32 v11, v11, v223
	v_mul_f32_e32 v12, v12, v224
	v_mul_f32_e32 v13, v13, v225
	v_mul_f32_e32 v14, v14, v226
	v_mul_f32_e32 v15, v15, v227
	v_mul_f32_e32 v16, v16, v228
	v_mul_f32_e32 v17, v17, v229
	v_mul_f32_e32 v18, v18, v230
	v_mul_f32_e32 v19, v19, v231
	v_mul_f32_e32 v20, v20, v232
	v_mul_f32_e32 v21, v21, v233
	v_mul_f32_e32 v22, v22, v234
	v_mul_f32_e32 v23, v23, v235
	v_mul_f32_e32 v24, v24, v236
	v_mul_f32_e32 v25, v25, v237
	v_mul_f32_e32 v26, v26, v238
	v_mul_f32_e32 v27, v27, v239
	v_mul_f32_e32 v36, v36, v240
	v_mul_f32_e32 v28, v28, v241
	v_mul_f32_e32 v29, v29, v242
	v_mul_f32_e32 v37, v37, v243
.Lxinit_done:
.LBB0_494:
	s_andn2_saveexec_b64 s[6:7], s[10:11]
	s_cbranch_execz .LBB0_496
	v_lshl_add_u32 v28, v31, 2, v168
	v_add_u32_e32 v37, 0xc300, v28
	ds_read2st64_b32 v[6:7], v28 offset0:233 offset1:234
	ds_read2st64_b32 v[8:9], v28 offset0:235 offset1:236
	ds_read2st64_b32 v[10:11], v28 offset0:237 offset1:238
	ds_read2st64_b32 v[12:13], v28 offset0:239 offset1:240
	ds_read2st64_b32 v[14:15], v28 offset0:241 offset1:242
	ds_read2st64_b32 v[16:17], v28 offset0:243 offset1:244
	ds_read2st64_b32 v[18:19], v28 offset0:245 offset1:246
	ds_read2st64_b32 v[20:21], v28 offset0:247 offset1:248
	ds_read2st64_b32 v[22:23], v28 offset0:249 offset1:250
	ds_read2st64_b32 v[24:25], v28 offset0:251 offset1:252
	ds_read2st64_b32 v[26:27], v28 offset0:253 offset1:254
	ds_read2st64_b32 v[0:1], v28 offset0:227 offset1:228
	ds_read2st64_b32 v[2:3], v28 offset0:229 offset1:230
	ds_read2st64_b32 v[4:5], v28 offset0:231 offset1:232
	ds_read_b32 v36, v28 offset:65280
	ds_read2st64_b32 v[28:29], v37 offset0:61 offset1:62
	ds_read_b32 v37, v37 offset:16128
